# P9 fix-up hand-written: the three elements of a thread are loaded together (48 loads in flight) before the arithmetic
# baseline (speedup 1.0000x reference)
; __global__ void __launch_bounds__(512, 2) mega_fwd(Args a) {
;     ...
;     for (int idx = gid; idx < 128 * DFF; idx += NT_ALL) {
;         const int pm = idx / DFF, j = idx - pm * DFF;
;         if ((pm & 15) == 0) continue;
;         const float* sp = SIDE + ((size_t)((pm - 1) * 4 + 2) * 2) * DFF + j;
;         const float* sc = SIDE + ((size_t)(pm * 4 + 0) * 2) * DFF + j;
;         const float p2a = sp[0], p2b = sp[DFF], p1a = sp[2 * DFF], p1b = sp[3 * DFF], x0a = sc[0], x0b = sc[DFF], x1a = sc[2 * DFF], x1b = sc[3 * DFF];
;         const float wa0 = KA->conv_w[j], wa1 = KA->conv_w[NUP + j], wa2 = KA->conv_w[2 * NUP + j], wb0 = KA->conv_w[DFF + j], wb1 = KA->conv_w[NUP + DFF + j], wb2 = KA->conv_w[2 * NUP + DFF + j];
;         const float ba = KA->conv_b[j], bb = KA->conv_b[DFF + j];
.LBB0_972:
	s_or_b64 exec, exec, s[6:7]
	s_mov_b64 s[6:7], s[0:1]
	s_waitcnt lgkmcnt(0)
	v_mov_b32_e32 v0, v195
	s_barrier
	s_load_dwordx2 s[20:21], s[6:7], 0xb8
	s_load_dwordx4 s[8:11], s[6:7], 0x98
	v_readlane_b32 s16, v255, 6
	s_nop 1
	v_add_u32_e32 v0, s16, v0
	s_mov_b32 s17, 0xba2e8ba3
	s_mov_b32 s18, 0x58000
	s_waitcnt lgkmcnt(0)
	s_add_u32 s36, s20, 0x6000000
	s_addc_u32 s37, s21, 0
	s_add_u32 s38, s20, 0x6002c00
	s_addc_u32 s39, s21, 0
	s_add_u32 s40, s20, 0x6005800
	s_addc_u32 s41, s21, 0
	s_add_u32 s42, s20, 0x6008400
	s_addc_u32 s43, s21, 0
	s_add_u32 s44, s20, 0x600b000
	s_addc_u32 s45, s21, 0
	s_add_u32 s46, s20, 0x600dc00
	s_addc_u32 s47, s21, 0
	s_add_u32 s48, s20, 0x6010800
	s_addc_u32 s49, s21, 0
	s_add_u32 s50, s20, 0x6013400
	s_addc_u32 s51, s21, 0
	s_add_u32 s52, s8, 0x0
	s_addc_u32 s53, s9, 0
	s_add_u32 s54, s8, 0x5800
	s_addc_u32 s55, s9, 0
	s_add_u32 s56, s8, 0xb000
	s_addc_u32 s57, s9, 0
	s_add_u32 s58, s8, 0x2c00
	s_addc_u32 s59, s9, 0
	s_add_u32 s60, s8, 0x8400
	s_addc_u32 s61, s9, 0
	s_add_u32 s62, s8, 0xdc00
	s_addc_u32 s63, s9, 0
	s_add_u32 s64, s10, 0x0
	s_addc_u32 s65, s11, 0
	s_add_u32 s66, s10, 0x2c00
	s_addc_u32 s67, s11, 0
	s_add_u32 s74, s20, 0x11000000
	s_addc_u32 s75, s21, 0
	s_add_u32 s76, s74, 0x1600
	s_addc_u32 s77, s75, 0
	v_mov_b32_e32 v1, v0
	v_lshrrev_b32_e32 v2, 8, v1
	v_mul_hi_u32 v4, v2, s17
	v_lshrrev_b32_e32 v4, 3, v4
	v_mul_u32_u24_e32 v2, 0xb00, v4
	v_sub_u32_e32 v7, v1, v2
	v_lshlrev_b32_e32 v7, 2, v7
	v_mul_u32_u24_e32 v10, 0x16000, v4
	v_add_u32_e32 v10, v10, v7
	v_add_u32_e32 v10, 0xffff5000, v10
	v_mov_b32_e32 v2, 0x160000
	v_mul_lo_u32 v13, v4, v2
	v_lshrrev_b32_e32 v2, 1, v7
	v_add_u32_e32 v13, v13, v2
	v_and_b32_e32 v2, 15, v4
	v_cmp_ne_u32_e32 vcc, 0, v2
	v_cmp_gt_u32_e64 s[68:69], s18, v1
	s_and_b64 s[68:69], s[68:69], vcc
	s_mov_b64 exec, s[68:69]
	global_load_dword v16, v10, s[36:37]
	global_load_dword v17, v10, s[38:39]
	global_load_dword v18, v10, s[40:41]
	global_load_dword v19, v10, s[42:43]
	global_load_dword v20, v10, s[44:45]
	global_load_dword v21, v10, s[46:47]
	global_load_dword v22, v10, s[48:49]
	global_load_dword v23, v10, s[50:51]
	global_load_dword v24, v7, s[52:53]
	global_load_dword v25, v7, s[54:55]
	global_load_dword v26, v7, s[56:57]
	global_load_dword v27, v7, s[58:59]
	global_load_dword v28, v7, s[60:61]
	global_load_dword v29, v7, s[62:63]
	global_load_dword v30, v7, s[64:65]
	global_load_dword v31, v7, s[66:67]
	s_mov_b64 exec, -1
	v_add_u32_e32 v1, 0x20000, v0
	v_lshrrev_b32_e32 v2, 8, v1
	v_mul_hi_u32 v5, v2, s17
	v_lshrrev_b32_e32 v5, 3, v5
	v_mul_u32_u24_e32 v2, 0xb00, v5
	v_sub_u32_e32 v8, v1, v2
	v_lshlrev_b32_e32 v8, 2, v8
	v_mul_u32_u24_e32 v11, 0x16000, v5
	v_add_u32_e32 v11, v11, v8
	v_add_u32_e32 v11, 0xffff5000, v11
	v_mov_b32_e32 v2, 0x160000
	v_mul_lo_u32 v14, v5, v2
	v_lshrrev_b32_e32 v2, 1, v8
	v_add_u32_e32 v14, v14, v2
	v_and_b32_e32 v2, 15, v5
	v_cmp_ne_u32_e32 vcc, 0, v2
	v_cmp_gt_u32_e64 s[70:71], s18, v1
	s_and_b64 s[70:71], s[70:71], vcc
	s_mov_b64 exec, s[70:71]
	global_load_dword v32, v11, s[36:37]
	global_load_dword v33, v11, s[38:39]
	global_load_dword v34, v11, s[40:41]
	global_load_dword v35, v11, s[42:43]
	global_load_dword v36, v11, s[44:45]
	global_load_dword v37, v11, s[46:47]
	global_load_dword v38, v11, s[48:49]
	global_load_dword v39, v11, s[50:51]
	global_load_dword v40, v8, s[52:53]
	global_load_dword v41, v8, s[54:55]
	global_load_dword v42, v8, s[56:57]
	global_load_dword v43, v8, s[58:59]
	global_load_dword v44, v8, s[60:61]
	global_load_dword v45, v8, s[62:63]
	global_load_dword v46, v8, s[64:65]
	global_load_dword v47, v8, s[66:67]
	s_mov_b64 exec, -1
	v_add_u32_e32 v1, 0x40000, v0
	v_lshrrev_b32_e32 v2, 8, v1
	v_mul_hi_u32 v6, v2, s17
	v_lshrrev_b32_e32 v6, 3, v6
	v_mul_u32_u24_e32 v2, 0xb00, v6
	v_sub_u32_e32 v9, v1, v2
	v_lshlrev_b32_e32 v9, 2, v9
	v_mul_u32_u24_e32 v12, 0x16000, v6
	v_add_u32_e32 v12, v12, v9
	v_add_u32_e32 v12, 0xffff5000, v12
	v_mov_b32_e32 v2, 0x160000
	v_mul_lo_u32 v15, v6, v2
	v_lshrrev_b32_e32 v2, 1, v9
	v_add_u32_e32 v15, v15, v2
	v_and_b32_e32 v2, 15, v6
	v_cmp_ne_u32_e32 vcc, 0, v2
	v_cmp_gt_u32_e64 s[72:73], s18, v1
	s_and_b64 s[72:73], s[72:73], vcc
	s_mov_b64 exec, s[72:73]
	global_load_dword v48, v12, s[36:37]
	global_load_dword v49, v12, s[38:39]
	global_load_dword v50, v12, s[40:41]
	global_load_dword v51, v12, s[42:43]
	global_load_dword v52, v12, s[44:45]
	global_load_dword v53, v12, s[46:47]
	global_load_dword v54, v12, s[48:49]
	global_load_dword v55, v12, s[50:51]
	global_load_dword v56, v9, s[52:53]
	global_load_dword v57, v9, s[54:55]
	global_load_dword v58, v9, s[56:57]
	global_load_dword v59, v9, s[58:59]
	global_load_dword v60, v9, s[60:61]
	global_load_dword v61, v9, s[62:63]
	global_load_dword v62, v9, s[64:65]
	global_load_dword v63, v9, s[66:67]
	s_mov_b64 exec, -1
	s_waitcnt vmcnt(0)
; __device__ __forceinline__ unsigned pk2(float lo, float hi) { f32x2_t v = {lo, hi}; bf16x2_t b = __builtin_convertvector(v, bf16x2_t); return __builtin_bit_cast(unsigned, b); }
; __device__ __forceinline__ float silu_f(float x) { return x * __builtin_amdgcn_rcpf(1.0f + __builtin_amdgcn_exp2f(-1.4426950408889634f * x)); }
; __global__ void __launch_bounds__(512, 2) mega_fwd(Args a) {
;     ...
;         const float ya0 = ba + wa0 * p2a + wa1 * p1a + wa2 * x0a, ya1 = ba + wa0 * p1a + wa1 * x0a + wa2 * x1a;
;         const float yb0 = bb + wb0 * p2b + wb1 * p1b + wb2 * x0b, yb1 = bb + wb0 * p1b + wb1 * x0b + wb2 * x1b;
;         ACT[(size_t)(pm * 256) * DFF + j] = (bf16_t)(pk2(silu_f(ya0) * yb0, 0.f) & 0xffffu);
;         ACT[(size_t)(pm * 256 + 1) * DFF + j] = (bf16_t)(pk2(silu_f(ya1) * yb1, 0.f) & 0xffffu);
	s_mov_b64 exec, s[68:69]
	v_fma_f32 v64, v16, v24, v30
	v_fma_f32 v65, v18, v24, v30
	v_fma_f32 v66, v17, v27, v31
	v_fma_f32 v67, v19, v27, v31
	v_fmac_f32_e32 v64, v18, v25
	v_fmac_f32_e32 v65, v20, v25
	v_fmac_f32_e32 v66, v19, v28
	v_fmac_f32_e32 v67, v21, v28
	v_fmac_f32_e32 v64, v20, v26
	v_fmac_f32_e32 v65, v22, v26
	v_fmac_f32_e32 v66, v21, v29
	v_fmac_f32_e32 v67, v23, v29
	v_mul_f32_e32 v68, 0xbfb8aa3b, v64
	v_mul_f32_e32 v69, 0xbfb8aa3b, v65
	v_exp_f32_e32 v68, v68
	v_exp_f32_e32 v69, v69
	s_nop 0
	v_add_f32_e32 v68, 1.0, v68
	v_add_f32_e32 v69, 1.0, v69
	v_rcp_f32_e32 v68, v68
	v_rcp_f32_e32 v69, v69
	s_nop 0
	v_mul_f32_e32 v68, v64, v68
	v_mul_f32_e32 v69, v65, v69
	v_mul_f32_e32 v68, v66, v68
	v_mul_f32_e32 v69, v67, v69
	v_cvt_pk_bf16_f32 v68, v68, v68
	v_cvt_pk_bf16_f32 v69, v69, v69
	global_store_short v13, v68, s[74:75]
	global_store_short v13, v69, s[76:77]
	s_mov_b64 exec, s[70:71]
	v_fma_f32 v64, v32, v40, v46
	v_fma_f32 v65, v34, v40, v46
	v_fma_f32 v66, v33, v43, v47
	v_fma_f32 v67, v35, v43, v47
	v_fmac_f32_e32 v64, v34, v41
	v_fmac_f32_e32 v65, v36, v41
	v_fmac_f32_e32 v66, v35, v44
	v_fmac_f32_e32 v67, v37, v44
	v_fmac_f32_e32 v64, v36, v42
	v_fmac_f32_e32 v65, v38, v42
	v_fmac_f32_e32 v66, v37, v45
	v_fmac_f32_e32 v67, v39, v45
	v_mul_f32_e32 v68, 0xbfb8aa3b, v64
	v_mul_f32_e32 v69, 0xbfb8aa3b, v65
	v_exp_f32_e32 v68, v68
	v_exp_f32_e32 v69, v69
	s_nop 0
	v_add_f32_e32 v68, 1.0, v68
	v_add_f32_e32 v69, 1.0, v69
	v_rcp_f32_e32 v68, v68
	v_rcp_f32_e32 v69, v69
	s_nop 0
	v_mul_f32_e32 v68, v64, v68
	v_mul_f32_e32 v69, v65, v69
	v_mul_f32_e32 v68, v66, v68
	v_mul_f32_e32 v69, v67, v69
	v_cvt_pk_bf16_f32 v68, v68, v68
	v_cvt_pk_bf16_f32 v69, v69, v69
	global_store_short v14, v68, s[74:75]
	global_store_short v14, v69, s[76:77]
	s_mov_b64 exec, s[72:73]
	v_fma_f32 v64, v48, v56, v62
	v_fma_f32 v65, v50, v56, v62
	v_fma_f32 v66, v49, v59, v63
	v_fma_f32 v67, v51, v59, v63
	v_fmac_f32_e32 v64, v50, v57
	v_fmac_f32_e32 v65, v52, v57
	v_fmac_f32_e32 v66, v51, v60
	v_fmac_f32_e32 v67, v53, v60
	v_fmac_f32_e32 v64, v52, v58
	v_fmac_f32_e32 v65, v54, v58
	v_fmac_f32_e32 v66, v53, v61
	v_fmac_f32_e32 v67, v55, v61
	v_mul_f32_e32 v68, 0xbfb8aa3b, v64
	v_mul_f32_e32 v69, 0xbfb8aa3b, v65
	v_exp_f32_e32 v68, v68
	v_exp_f32_e32 v69, v69
	s_nop 0
	v_add_f32_e32 v68, 1.0, v68
	v_add_f32_e32 v69, 1.0, v69
	v_rcp_f32_e32 v68, v68
	v_rcp_f32_e32 v69, v69
	s_nop 0
	v_mul_f32_e32 v68, v64, v68
	v_mul_f32_e32 v69, v65, v69
	v_mul_f32_e32 v68, v66, v68
	v_mul_f32_e32 v69, v67, v69
	v_cvt_pk_bf16_f32 v68, v68, v68
	v_cvt_pk_bf16_f32 v69, v69, v69
	global_store_short v15, v68, s[74:75]
	global_store_short v15, v69, s[76:77]
	s_mov_b64 exec, -1
